# MLP-up: MFMA blocks of structurally-zero padding rows (row tile 32: A half 1, and wr=1 waves) are branched over; bit-exact
# speedup vs baseline: 1.0046x; 1.0046x over previous
.LBB0_707:
	s_ashr_i32 s45, s44, 31
	s_lshl_b64 s[46:47], s[44:45], 20
	s_add_u32 s46, s80, s46
	s_addc_u32 s47, s81, s47
	s_and_b64 s[48:49], s[38:39], exec
	s_cselect_b32 s41, s47, s87
	s_cselect_b32 s45, s46, s86
	s_ashr_i32 s43, s42, 31
	s_lshl_b64 s[48:49], s[42:43], 20
	s_add_u32 s48, s56, s48
	s_addc_u32 s49, s55, s49
	s_and_b64 s[64:65], s[38:39], exec
	s_cselect_b32 s43, s49, s9
	s_cselect_b32 s63, s48, s8
	s_add_u32 s86, s86, 0x80080
	s_addc_u32 s87, s87, 0
	s_add_u32 s64, s8, 0x100
	v_mov_b32_e32 v2, 0
	s_addc_u32 s65, s9, 0
	s_mov_b32 s66, -2
	v_mov_b32_e32 v3, v2
	v_mov_b32_e32 v4, v2
	v_mov_b32_e32 v5, v2
	v_mov_b32_e32 v6, v2
	v_mov_b32_e32 v7, v2
	v_mov_b32_e32 v8, v2
	v_mov_b32_e32 v9, v2
	v_mov_b32_e32 v18, v2
	v_mov_b32_e32 v19, v2
	v_mov_b32_e32 v20, v2
	v_mov_b32_e32 v21, v2
	v_mov_b32_e32 v22, v2
	v_mov_b32_e32 v23, v2
	v_mov_b32_e32 v24, v2
	v_mov_b32_e32 v25, v2
	v_mov_b32_e32 v34, v2
	v_mov_b32_e32 v35, v2
	v_mov_b32_e32 v36, v2
	v_mov_b32_e32 v37, v2
	v_mov_b32_e32 v38, v2
	v_mov_b32_e32 v39, v2
	v_mov_b32_e32 v40, v2
	v_mov_b32_e32 v41, v2
	v_mov_b32_e32 v50, v2
	v_mov_b32_e32 v51, v2
	v_mov_b32_e32 v52, v2
	v_mov_b32_e32 v53, v2
	v_mov_b32_e32 v54, v2
	v_mov_b32_e32 v55, v2
	v_mov_b32_e32 v56, v2
	v_mov_b32_e32 v57, v2
	v_mov_b32_e32 v10, v2
	v_mov_b32_e32 v11, v2
	v_mov_b32_e32 v12, v2
	v_mov_b32_e32 v13, v2
	v_mov_b32_e32 v14, v2
	v_mov_b32_e32 v15, v2
	v_mov_b32_e32 v16, v2
	v_mov_b32_e32 v17, v2
	v_mov_b32_e32 v26, v2
	v_mov_b32_e32 v27, v2
	v_mov_b32_e32 v28, v2
	v_mov_b32_e32 v29, v2
	v_mov_b32_e32 v30, v2
	v_mov_b32_e32 v31, v2
	v_mov_b32_e32 v32, v2
	v_mov_b32_e32 v33, v2
	v_mov_b32_e32 v42, v2
	v_mov_b32_e32 v43, v2
	v_mov_b32_e32 v44, v2
	v_mov_b32_e32 v45, v2
	v_mov_b32_e32 v46, v2
	v_mov_b32_e32 v47, v2
	v_mov_b32_e32 v48, v2
	v_mov_b32_e32 v49, v2
	v_mov_b32_e32 v58, v2
	v_mov_b32_e32 v59, v2
	v_mov_b32_e32 v60, v2
	v_mov_b32_e32 v61, v2
	v_mov_b32_e32 v62, v2
	v_mov_b32_e32 v63, v2
	v_mov_b32_e32 v64, v2
	v_mov_b32_e32 v65, v2
	v_mov_b32_e32 v66, v2
	v_mov_b32_e32 v67, v2
	v_mov_b32_e32 v68, v2
	v_mov_b32_e32 v69, v2
	v_mov_b32_e32 v70, v2
	v_mov_b32_e32 v71, v2
	v_mov_b32_e32 v72, v2
	v_mov_b32_e32 v73, v2
	v_mov_b32_e32 v82, v2
	v_mov_b32_e32 v83, v2
	v_mov_b32_e32 v84, v2
	v_mov_b32_e32 v85, v2
	v_mov_b32_e32 v86, v2
	v_mov_b32_e32 v87, v2
	v_mov_b32_e32 v88, v2
	v_mov_b32_e32 v89, v2
	v_mov_b32_e32 v98, v2
	v_mov_b32_e32 v99, v2
	v_mov_b32_e32 v100, v2
	v_mov_b32_e32 v101, v2
	v_mov_b32_e32 v102, v2
	v_mov_b32_e32 v103, v2
	v_mov_b32_e32 v104, v2
	v_mov_b32_e32 v105, v2
	v_mov_b32_e32 v120, v2
	v_mov_b32_e32 v121, v2
	v_mov_b32_e32 v122, v2
	v_mov_b32_e32 v123, v2
	v_mov_b32_e32 v124, v2
	v_mov_b32_e32 v125, v2
	v_mov_b32_e32 v126, v2
	v_mov_b32_e32 v127, v2
	v_mov_b32_e32 v74, v2
	v_mov_b32_e32 v75, v2
	v_mov_b32_e32 v76, v2
	v_mov_b32_e32 v77, v2
	v_mov_b32_e32 v78, v2
	v_mov_b32_e32 v79, v2
	v_mov_b32_e32 v80, v2
	v_mov_b32_e32 v81, v2
	v_mov_b32_e32 v90, v2
	v_mov_b32_e32 v91, v2
	v_mov_b32_e32 v92, v2
	v_mov_b32_e32 v93, v2
	v_mov_b32_e32 v94, v2
	v_mov_b32_e32 v95, v2
	v_mov_b32_e32 v96, v2
	v_mov_b32_e32 v97, v2
	v_mov_b32_e32 v106, v2
	v_mov_b32_e32 v107, v2
	v_mov_b32_e32 v108, v2
	v_mov_b32_e32 v109, v2
	v_mov_b32_e32 v116, v2
	v_mov_b32_e32 v117, v2
	v_mov_b32_e32 v118, v2
	v_mov_b32_e32 v119, v2
	v_mov_b32_e32 v128, v2
	v_mov_b32_e32 v129, v2
	v_mov_b32_e32 v130, v2
	v_mov_b32_e32 v131, v2
	v_mov_b32_e32 v132, v2
	v_mov_b32_e32 v133, v2
	v_mov_b32_e32 v134, v2
	v_mov_b32_e32 v135, v2
	s_cmp_eq_u32 s84, 32
	s_cselect_b32 s98, 3, 0
	s_and_b32 s99, s16, 1
	s_andn2_b32 s98, s98, s99
.LBB0_708:
	s_add_u32 s8, s86, 0xfff80080
	s_addc_u32 s9, s87, -1
	s_add_i32 s67, 0, 0x10000
	s_cmp_eq_u32 s66, 28
	s_cselect_b32 s93, s41, s9
	s_cselect_b32 s92, s45, s8
	v_add_u32_e32 v150, s67, v152
	s_cselect_b32 s9, s43, s65
	s_cselect_b32 s8, s63, s64
	s_add_i32 s70, 0, 0x14000
	ds_read_b128 v[146:149], v150
	ds_read_b128 v[156:159], v150 offset:1024
	ds_read_b128 v[160:163], v150 offset:2048
	ds_read_b128 v[170:173], v150 offset:3072
	v_add_u32_e32 v150, s70, v152
	ds_read_b128 v[184:187], v150
	ds_read_b128 v[188:191], v150 offset:1024
	ds_read_b128 v[192:195], v150 offset:2048
	ds_read_b128 v[196:199], v150 offset:3072
	v_lshl_add_u64 v[150:151], s[86:87], 0, v[142:143]
	s_add_i32 m0, s57, 0xc000
	ds_read_b128 v[214:217], v154
	ds_read_b128 v[218:221], v154 offset:1024
	ds_read_b128 v[222:225], v154 offset:2048
	ds_read_b128 v[226:229], v154 offset:3072
	ds_read_b128 v[230:233], v154 offset:4096
	ds_read_b128 v[234:237], v154 offset:5120
	ds_read_b128 v[238:241], v154 offset:6144
	ds_read_b128 v[242:245], v154 offset:7168
	global_load_lds_dwordx4 v[150:151], off
	v_lshl_add_u64 v[150:151], s[86:87], 0, v[144:145]
	s_add_i32 m0, s57, 0xe000
	s_nop 0
	global_load_lds_dwordx4 v[150:151], off
	s_waitcnt vmcnt(8)
	s_waitcnt lgkmcnt(0)
	s_barrier
	s_setprio 1
	s_bitcmp1_b32 s98, 0
	s_cbranch_scc1 .Lmy_ps_mlpup_0
	v_mfma_f32_16x16x32_bf16 v[132:135], v[146:149], v[214:217], v[132:135]
	v_mfma_f32_16x16x32_bf16 v[128:131], v[160:163], v[214:217], v[128:131]
	v_mfma_f32_16x16x32_bf16 v[116:119], v[146:149], v[222:225], v[116:119]
	v_mfma_f32_16x16x32_bf16 v[106:109], v[160:163], v[222:225], v[106:109]
	v_mfma_f32_16x16x32_bf16 v[94:97], v[146:149], v[230:233], v[94:97]
	v_mfma_f32_16x16x32_bf16 v[90:93], v[160:163], v[230:233], v[90:93]
	v_mfma_f32_16x16x32_bf16 v[78:81], v[146:149], v[238:241], v[78:81]
	v_mfma_f32_16x16x32_bf16 v[74:77], v[160:163], v[238:241], v[74:77]
	v_mfma_f32_16x16x32_bf16 v[132:135], v[156:159], v[218:221], v[132:135]
	v_mfma_f32_16x16x32_bf16 v[128:131], v[170:173], v[218:221], v[128:131]
	v_mfma_f32_16x16x32_bf16 v[116:119], v[156:159], v[226:229], v[116:119]
	v_mfma_f32_16x16x32_bf16 v[106:109], v[170:173], v[226:229], v[106:109]
	v_mfma_f32_16x16x32_bf16 v[94:97], v[156:159], v[234:237], v[94:97]
	v_mfma_f32_16x16x32_bf16 v[90:93], v[170:173], v[234:237], v[90:93]
	v_mfma_f32_16x16x32_bf16 v[78:81], v[156:159], v[242:245], v[78:81]
	v_mfma_f32_16x16x32_bf16 v[74:77], v[170:173], v[242:245], v[74:77]
	v_mfma_f32_16x16x32_bf16 v[124:127], v[184:187], v[214:217], v[124:127]
	v_mfma_f32_16x16x32_bf16 v[120:123], v[192:195], v[214:217], v[120:123]
	v_mfma_f32_16x16x32_bf16 v[102:105], v[184:187], v[222:225], v[102:105]
	v_mfma_f32_16x16x32_bf16 v[98:101], v[192:195], v[222:225], v[98:101]
	v_mfma_f32_16x16x32_bf16 v[86:89], v[184:187], v[230:233], v[86:89]
	v_mfma_f32_16x16x32_bf16 v[82:85], v[192:195], v[230:233], v[82:85]
	v_mfma_f32_16x16x32_bf16 v[70:73], v[184:187], v[238:241], v[70:73]
	v_mfma_f32_16x16x32_bf16 v[66:69], v[192:195], v[238:241], v[66:69]
	v_mfma_f32_16x16x32_bf16 v[124:127], v[188:191], v[218:221], v[124:127]
	v_mfma_f32_16x16x32_bf16 v[120:123], v[196:199], v[218:221], v[120:123]
	v_mfma_f32_16x16x32_bf16 v[102:105], v[188:191], v[226:229], v[102:105]
	v_mfma_f32_16x16x32_bf16 v[98:101], v[196:199], v[226:229], v[98:101]
	v_mfma_f32_16x16x32_bf16 v[86:89], v[188:191], v[234:237], v[86:89]
	v_mfma_f32_16x16x32_bf16 v[82:85], v[196:199], v[234:237], v[82:85]
	v_mfma_f32_16x16x32_bf16 v[70:73], v[188:191], v[242:245], v[70:73]
	v_mfma_f32_16x16x32_bf16 v[66:69], v[196:199], v[242:245], v[66:69]
.Lmy_ps_mlpup_0:
	s_setprio 0
	s_barrier
	s_add_i32 s67, s67, s54
	v_lshl_add_u64 v[150:151], s[8:9], 0, v[136:137]
	s_mov_b32 m0, s67
	ds_read_b128 v[214:217], v154 offset:16384
	ds_read_b128 v[218:221], v154 offset:17408
	ds_read_b128 v[222:225], v154 offset:18432
	ds_read_b128 v[226:229], v154 offset:19456
	ds_read_b128 v[230:233], v154 offset:20480
	ds_read_b128 v[234:237], v154 offset:21504
	ds_read_b128 v[238:241], v154 offset:22528
	ds_read_b128 v[242:245], v154 offset:23552
	global_load_lds_dwordx4 v[150:151], off
	s_add_i32 m0, s67, 0x2000
	s_add_u32 s68, s8, 0x80000
	v_lshl_add_u64 v[200:201], s[8:9], 0, v[140:141]
	s_addc_u32 s69, s9, 0
	s_add_i32 s67, s70, s54
	global_load_lds_dwordx4 v[200:201], off
	v_lshl_add_u64 v[206:207], s[68:69], 0, v[136:137]
	s_mov_b32 m0, s67
	v_lshl_add_u64 v[246:247], s[92:93], 0, v[138:139]
	global_load_lds_dwordx4 v[206:207], off
	v_lshl_add_u64 v[206:207], s[68:69], 0, v[140:141]
	s_add_i32 m0, s67, 0x2000
	s_nop 0
	global_load_lds_dwordx4 v[206:207], off
	v_lshl_add_u64 v[206:207], s[92:93], 0, v[110:111]
	s_mov_b32 m0, s57
	s_nop 0
	global_load_lds_dwordx4 v[206:207], off
	s_mov_b32 m0, s58
	s_nop 0
	global_load_lds_dwordx4 v[246:247], off
	s_waitcnt vmcnt(8)
	s_waitcnt lgkmcnt(0)
	s_barrier
	s_setprio 1
	s_bitcmp1_b32 s98, 1
	s_cbranch_scc1 .Lmy_ps_mlpup_1
	v_mfma_f32_16x16x32_bf16 v[62:65], v[146:149], v[214:217], v[62:65]
	v_mfma_f32_16x16x32_bf16 v[58:61], v[160:163], v[214:217], v[58:61]
	v_mfma_f32_16x16x32_bf16 v[46:49], v[146:149], v[222:225], v[46:49]
	v_mfma_f32_16x16x32_bf16 v[42:45], v[160:163], v[222:225], v[42:45]
	v_mfma_f32_16x16x32_bf16 v[30:33], v[146:149], v[230:233], v[30:33]
	v_mfma_f32_16x16x32_bf16 v[26:29], v[160:163], v[230:233], v[26:29]
	v_mfma_f32_16x16x32_bf16 v[14:17], v[146:149], v[238:241], v[14:17]
	v_mfma_f32_16x16x32_bf16 v[10:13], v[160:163], v[238:241], v[10:13]
	v_mfma_f32_16x16x32_bf16 v[62:65], v[156:159], v[218:221], v[62:65]
	v_mfma_f32_16x16x32_bf16 v[58:61], v[170:173], v[218:221], v[58:61]
	v_mfma_f32_16x16x32_bf16 v[46:49], v[156:159], v[226:229], v[46:49]
	v_mfma_f32_16x16x32_bf16 v[42:45], v[170:173], v[226:229], v[42:45]
	v_mfma_f32_16x16x32_bf16 v[30:33], v[156:159], v[234:237], v[30:33]
	v_mfma_f32_16x16x32_bf16 v[26:29], v[170:173], v[234:237], v[26:29]
	v_mfma_f32_16x16x32_bf16 v[14:17], v[156:159], v[242:245], v[14:17]
	v_mfma_f32_16x16x32_bf16 v[10:13], v[170:173], v[242:245], v[10:13]
	v_mfma_f32_16x16x32_bf16 v[54:57], v[184:187], v[214:217], v[54:57]
	v_mfma_f32_16x16x32_bf16 v[50:53], v[192:195], v[214:217], v[50:53]
	v_mfma_f32_16x16x32_bf16 v[38:41], v[184:187], v[222:225], v[38:41]
	v_mfma_f32_16x16x32_bf16 v[34:37], v[192:195], v[222:225], v[34:37]
	v_mfma_f32_16x16x32_bf16 v[22:25], v[184:187], v[230:233], v[22:25]
	v_mfma_f32_16x16x32_bf16 v[18:21], v[192:195], v[230:233], v[18:21]
	v_mfma_f32_16x16x32_bf16 v[6:9], v[184:187], v[238:241], v[6:9]
	v_mfma_f32_16x16x32_bf16 v[2:5], v[192:195], v[238:241], v[2:5]
	v_mfma_f32_16x16x32_bf16 v[54:57], v[188:191], v[218:221], v[54:57]
	v_mfma_f32_16x16x32_bf16 v[50:53], v[196:199], v[218:221], v[50:53]
	v_mfma_f32_16x16x32_bf16 v[38:41], v[188:191], v[226:229], v[38:41]
	v_mfma_f32_16x16x32_bf16 v[34:37], v[196:199], v[226:229], v[34:37]
	v_mfma_f32_16x16x32_bf16 v[22:25], v[188:191], v[234:237], v[22:25]
	v_mfma_f32_16x16x32_bf16 v[18:21], v[196:199], v[234:237], v[18:21]
	v_mfma_f32_16x16x32_bf16 v[6:9], v[188:191], v[242:245], v[6:9]
	v_mfma_f32_16x16x32_bf16 v[2:5], v[196:199], v[242:245], v[2:5]
.Lmy_ps_mlpup_1:
	s_setprio 0
	s_barrier
	s_add_i32 s67, 0, 0x18000
	v_add_u32_e32 v155, s67, v152
	s_add_i32 s70, 0, 0x1c000
	ds_read_b128 v[146:149], v155
	ds_read_b128 v[156:159], v155 offset:1024
	ds_read_b128 v[160:163], v155 offset:2048
	ds_read_b128 v[170:173], v155 offset:3072
	v_add_u32_e32 v155, s70, v152
	ds_read_b128 v[184:187], v155
	ds_read_b128 v[188:191], v155 offset:1024
	ds_read_b128 v[192:195], v155 offset:2048
	ds_read_b128 v[196:199], v155 offset:3072
	s_add_u32 s68, s92, 0x80000
	s_addc_u32 s69, s93, 0
	s_mov_b32 m0, s59
	v_lshl_add_u64 v[248:249], s[68:69], 0, v[110:111]
	ds_read_b128 v[214:217], v154 offset:32768
	ds_read_b128 v[218:221], v154 offset:33792
	ds_read_b128 v[222:225], v154 offset:34816
	ds_read_b128 v[226:229], v154 offset:35840
	ds_read_b128 v[230:233], v154 offset:36864
	ds_read_b128 v[234:237], v154 offset:37888
	ds_read_b128 v[238:241], v154 offset:38912
	ds_read_b128 v[242:245], v154 offset:39936
	global_load_lds_dwordx4 v[248:249], off
	v_lshl_add_u64 v[248:249], s[68:69], 0, v[138:139]
	s_mov_b32 m0, s60
	s_nop 0
	global_load_lds_dwordx4 v[248:249], off
	s_waitcnt vmcnt(8)
	s_waitcnt lgkmcnt(0)
	s_barrier
	s_setprio 1
	s_bitcmp1_b32 s98, 0
	s_cbranch_scc1 .Lmy_ps_mlpup_2
	v_mfma_f32_16x16x32_bf16 v[132:135], v[146:149], v[214:217], v[132:135]
	v_mfma_f32_16x16x32_bf16 v[128:131], v[160:163], v[214:217], v[128:131]
	v_mfma_f32_16x16x32_bf16 v[116:119], v[146:149], v[222:225], v[116:119]
	v_mfma_f32_16x16x32_bf16 v[106:109], v[160:163], v[222:225], v[106:109]
	v_mfma_f32_16x16x32_bf16 v[94:97], v[146:149], v[230:233], v[94:97]
	v_mfma_f32_16x16x32_bf16 v[90:93], v[160:163], v[230:233], v[90:93]
	v_mfma_f32_16x16x32_bf16 v[78:81], v[146:149], v[238:241], v[78:81]
	v_mfma_f32_16x16x32_bf16 v[74:77], v[160:163], v[238:241], v[74:77]
	v_mfma_f32_16x16x32_bf16 v[132:135], v[156:159], v[218:221], v[132:135]
	v_mfma_f32_16x16x32_bf16 v[128:131], v[170:173], v[218:221], v[128:131]
	v_mfma_f32_16x16x32_bf16 v[116:119], v[156:159], v[226:229], v[116:119]
	v_mfma_f32_16x16x32_bf16 v[106:109], v[170:173], v[226:229], v[106:109]
	v_mfma_f32_16x16x32_bf16 v[94:97], v[156:159], v[234:237], v[94:97]
	v_mfma_f32_16x16x32_bf16 v[90:93], v[170:173], v[234:237], v[90:93]
	v_mfma_f32_16x16x32_bf16 v[78:81], v[156:159], v[242:245], v[78:81]
	v_mfma_f32_16x16x32_bf16 v[74:77], v[170:173], v[242:245], v[74:77]
	v_mfma_f32_16x16x32_bf16 v[124:127], v[184:187], v[214:217], v[124:127]
	v_mfma_f32_16x16x32_bf16 v[120:123], v[192:195], v[214:217], v[120:123]
	v_mfma_f32_16x16x32_bf16 v[102:105], v[184:187], v[222:225], v[102:105]
	v_mfma_f32_16x16x32_bf16 v[98:101], v[192:195], v[222:225], v[98:101]
	v_mfma_f32_16x16x32_bf16 v[86:89], v[184:187], v[230:233], v[86:89]
	v_mfma_f32_16x16x32_bf16 v[82:85], v[192:195], v[230:233], v[82:85]
	v_mfma_f32_16x16x32_bf16 v[70:73], v[184:187], v[238:241], v[70:73]
	v_mfma_f32_16x16x32_bf16 v[66:69], v[192:195], v[238:241], v[66:69]
	v_mfma_f32_16x16x32_bf16 v[124:127], v[188:191], v[218:221], v[124:127]
	v_mfma_f32_16x16x32_bf16 v[120:123], v[196:199], v[218:221], v[120:123]
	v_mfma_f32_16x16x32_bf16 v[102:105], v[188:191], v[226:229], v[102:105]
	v_mfma_f32_16x16x32_bf16 v[98:101], v[196:199], v[226:229], v[98:101]
	v_mfma_f32_16x16x32_bf16 v[86:89], v[188:191], v[234:237], v[86:89]
	v_mfma_f32_16x16x32_bf16 v[82:85], v[196:199], v[234:237], v[82:85]
	v_mfma_f32_16x16x32_bf16 v[70:73], v[188:191], v[242:245], v[70:73]
	v_mfma_f32_16x16x32_bf16 v[66:69], v[196:199], v[242:245], v[66:69]
.Lmy_ps_mlpup_2:
	s_setprio 0
	s_barrier
	s_add_i32 s67, s67, s54
	v_lshl_add_u64 v[150:151], v[150:151], 0, s[26:27]
	s_mov_b32 m0, s67
	ds_read_b128 v[214:217], v154 offset:49152
	ds_read_b128 v[218:221], v154 offset:50176
	ds_read_b128 v[222:225], v154 offset:51200
	ds_read_b128 v[226:229], v154 offset:52224
	ds_read_b128 v[230:233], v154 offset:53248
	ds_read_b128 v[234:237], v154 offset:54272
	ds_read_b128 v[238:241], v154 offset:55296
	ds_read_b128 v[242:245], v154 offset:56320
	global_load_lds_dwordx4 v[150:151], off
	s_add_i32 m0, s67, 0x2000
	s_add_u32 s8, s8, 0x80080
	v_lshl_add_u64 v[150:151], v[200:201], 0, s[26:27]
	s_addc_u32 s9, s9, 0
	s_add_i32 s67, s70, s54
	global_load_lds_dwordx4 v[150:151], off
	v_lshl_add_u64 v[150:151], s[8:9], 0, v[136:137]
	s_mov_b32 m0, s67
	s_nop 0
	global_load_lds_dwordx4 v[150:151], off
	v_lshl_add_u64 v[150:151], s[8:9], 0, v[140:141]
	s_add_i32 m0, s67, 0x2000
	s_nop 0
	global_load_lds_dwordx4 v[150:151], off
	v_lshl_add_u64 v[150:151], v[206:207], 0, s[26:27]
	s_mov_b32 m0, s37
	s_nop 0
	global_load_lds_dwordx4 v[150:151], off
	v_lshl_add_u64 v[150:151], v[246:247], 0, s[26:27]
	s_mov_b32 m0, s61
	s_nop 0
	global_load_lds_dwordx4 v[150:151], off
	s_waitcnt vmcnt(8)
	s_waitcnt lgkmcnt(0)
	s_barrier
	s_setprio 1
	s_bitcmp1_b32 s98, 1
	s_cbranch_scc1 .Lmy_ps_mlpup_3
	v_mfma_f32_16x16x32_bf16 v[62:65], v[146:149], v[214:217], v[62:65]
	v_mfma_f32_16x16x32_bf16 v[58:61], v[160:163], v[214:217], v[58:61]
	v_mfma_f32_16x16x32_bf16 v[46:49], v[146:149], v[222:225], v[46:49]
	v_mfma_f32_16x16x32_bf16 v[42:45], v[160:163], v[222:225], v[42:45]
	v_mfma_f32_16x16x32_bf16 v[30:33], v[146:149], v[230:233], v[30:33]
	v_mfma_f32_16x16x32_bf16 v[26:29], v[160:163], v[230:233], v[26:29]
	v_mfma_f32_16x16x32_bf16 v[14:17], v[146:149], v[238:241], v[14:17]
	v_mfma_f32_16x16x32_bf16 v[10:13], v[160:163], v[238:241], v[10:13]
	v_mfma_f32_16x16x32_bf16 v[62:65], v[156:159], v[218:221], v[62:65]
	v_mfma_f32_16x16x32_bf16 v[58:61], v[170:173], v[218:221], v[58:61]
	v_mfma_f32_16x16x32_bf16 v[46:49], v[156:159], v[226:229], v[46:49]
	v_mfma_f32_16x16x32_bf16 v[42:45], v[170:173], v[226:229], v[42:45]
	v_mfma_f32_16x16x32_bf16 v[30:33], v[156:159], v[234:237], v[30:33]
	v_mfma_f32_16x16x32_bf16 v[26:29], v[170:173], v[234:237], v[26:29]
	v_mfma_f32_16x16x32_bf16 v[14:17], v[156:159], v[242:245], v[14:17]
	v_mfma_f32_16x16x32_bf16 v[10:13], v[170:173], v[242:245], v[10:13]
	v_mfma_f32_16x16x32_bf16 v[54:57], v[184:187], v[214:217], v[54:57]
	v_mfma_f32_16x16x32_bf16 v[50:53], v[192:195], v[214:217], v[50:53]
	v_mfma_f32_16x16x32_bf16 v[38:41], v[184:187], v[222:225], v[38:41]
	v_mfma_f32_16x16x32_bf16 v[34:37], v[192:195], v[222:225], v[34:37]
	v_mfma_f32_16x16x32_bf16 v[22:25], v[184:187], v[230:233], v[22:25]
	v_mfma_f32_16x16x32_bf16 v[18:21], v[192:195], v[230:233], v[18:21]
	v_mfma_f32_16x16x32_bf16 v[6:9], v[184:187], v[238:241], v[6:9]
	v_mfma_f32_16x16x32_bf16 v[2:5], v[192:195], v[238:241], v[2:5]
	v_mfma_f32_16x16x32_bf16 v[54:57], v[188:191], v[218:221], v[54:57]
	v_mfma_f32_16x16x32_bf16 v[50:53], v[196:199], v[218:221], v[50:53]
	v_mfma_f32_16x16x32_bf16 v[38:41], v[188:191], v[226:229], v[38:41]
	v_mfma_f32_16x16x32_bf16 v[34:37], v[196:199], v[226:229], v[34:37]
	v_mfma_f32_16x16x32_bf16 v[22:25], v[188:191], v[234:237], v[22:25]
	v_mfma_f32_16x16x32_bf16 v[18:21], v[196:199], v[234:237], v[18:21]
	v_mfma_f32_16x16x32_bf16 v[6:9], v[188:191], v[242:245], v[6:9]
	v_mfma_f32_16x16x32_bf16 v[2:5], v[196:199], v[242:245], v[2:5]
.Lmy_ps_mlpup_3:
	s_setprio 0
	s_barrier
	s_add_i32 s66, s66, 2
	s_add_u32 s86, s86, 0x100
	s_addc_u32 s87, s87, 0
	s_add_u32 s64, s64, 0x100
	s_addc_u32 s65, s65, 0
	s_cmp_gt_u32 s66, 29
	s_cbranch_scc0 .LBB0_708
	s_and_b64 vcc, exec, s[16:17]
	s_cbranch_vccz .LBB0_711
	s_barrier

	.amdhsa_kernel _Z10fwd_kernel4Args
		.amdhsa_group_segment_fixed_size 0
		.amdhsa_private_segment_fixed_size 0
		.amdhsa_kernarg_size 400
		.amdhsa_user_sgpr_count 2
		.amdhsa_user_sgpr_dispatch_ptr 0
		.amdhsa_user_sgpr_queue_ptr 0
		.amdhsa_user_sgpr_kernarg_segment_ptr 1
		.amdhsa_user_sgpr_dispatch_id 0
		.amdhsa_user_sgpr_kernarg_preload_length 0
		.amdhsa_user_sgpr_kernarg_preload_offset 0
		.amdhsa_user_sgpr_private_segment_size 0
		.amdhsa_uses_dynamic_stack 0
		.amdhsa_enable_private_segment 0
		.amdhsa_system_sgpr_workgroup_id_x 1
		.amdhsa_system_sgpr_workgroup_id_y 0
		.amdhsa_system_sgpr_workgroup_id_z 0
		.amdhsa_system_sgpr_workgroup_info 0
		.amdhsa_system_vgpr_workitem_id 2
		.amdhsa_next_free_vgpr 256
		.amdhsa_next_free_sgpr 102
		.amdhsa_accum_offset 256
		.amdhsa_reserve_vcc 1
		.amdhsa_float_round_mode_32 0
		.amdhsa_float_round_mode_16_64 0
		.amdhsa_float_denorm_mode_32 3
		.amdhsa_float_denorm_mode_16_64 3
		.amdhsa_dx10_clamp 1
		.amdhsa_ieee_mode 1
		.amdhsa_fp16_overflow 0
		.amdhsa_tg_split 0
		.amdhsa_exception_fp_ieee_invalid_op 0
		.amdhsa_exception_fp_denorm_src 0
		.amdhsa_exception_fp_ieee_div_zero 0
		.amdhsa_exception_fp_ieee_overflow 0
		.amdhsa_exception_fp_ieee_underflow 0
		.amdhsa_exception_fp_ieee_inexact 0
		.amdhsa_exception_int_div_zero 0
	.end_amdhsa_kernel

amdhsa.kernels:
  - .agpr_count:     0
    .args:
      - .offset:         0
        .size:           144
        .value_kind:     by_value
      - .offset:         144
        .size:           4
        .value_kind:     hidden_block_count_x
      - .offset:         148
        .size:           4
        .value_kind:     hidden_block_count_y
      - .offset:         152
        .size:           4
        .value_kind:     hidden_block_count_z
      - .offset:         156
        .size:           2
        .value_kind:     hidden_group_size_x
      - .offset:         158
        .size:           2
        .value_kind:     hidden_group_size_y
      - .offset:         160
        .size:           2
        .value_kind:     hidden_group_size_z
      - .offset:         162
        .size:           2
        .value_kind:     hidden_remainder_x
      - .offset:         164
        .size:           2
        .value_kind:     hidden_remainder_y
      - .offset:         166
        .size:           2
        .value_kind:     hidden_remainder_z
      - .offset:         184
        .size:           8
        .value_kind:     hidden_global_offset_x
      - .offset:         192
        .size:           8
        .value_kind:     hidden_global_offset_y
      - .offset:         200
        .size:           8
        .value_kind:     hidden_global_offset_z
      - .offset:         208
        .size:           2
        .value_kind:     hidden_grid_dims
      - .offset:         232
        .size:           8
        .value_kind:     hidden_multigrid_sync_arg
      - .offset:         264
        .size:           4
        .value_kind:     hidden_dynamic_lds_size
    .group_segment_fixed_size: 0
    .kernarg_segment_align: 8
    .kernarg_segment_size: 400
    .language:       OpenCL C
    .language_version:
      - 2
      - 0
    .max_flat_workgroup_size: 512
    .name:           _Z10fwd_kernel4Args
    .private_segment_fixed_size: 0
    .sgpr_count:     108
    .sgpr_spill_count: 219
    .symbol:         _Z10fwd_kernel4Args.kd
    .uniform_work_group_size: 1
    .uses_dynamic_stack: false
    .vgpr_count:     256
    .vgpr_spill_count: 0
    .wavefront_size: 64
